# v77 + GEMM unit decode: division by the (always 4) group size replaced by shift/mask in all four GEMM phases (27 fewer scalar instructions and one VALU->SGPR round trip per unit)
# baseline (speedup 1.0000x reference)
;     __host__ __device__ bool next(int i, Unit& u) const {
;         const long L = (long)i * G + c; if (L >= nwg) return false;
;         int wgid = (int)L; { const int q = nwg / NXCD, r = nwg % NXCD, xcd = wgid % NXCD, off = wgid / NXCD; wgid = (xcd < r ? xcd * (q + 1) : r * (q + 1) + (xcd - r) * q) + off; }
;         const int nig = WGM * nN, gid = wgid / nig, fm = gid * WGM, gsz = (nM - fm) < WGM ? (nM - fm) : WGM;
;         u.pm = fm + ((wgid % nig) % gsz); u.pn = (wgid % nig) / gsz; return true;
.LBB0_185:
	s_add_i32 s67, s6, 1
	v_readlane_b32 s14, v254, 8
	s_mul_i32 s14, s67, s14
	s_mul_hi_u32 s15, s67, s26
	s_add_i32 s15, s15, s14
	s_mul_i32 s14, s67, s26
	v_readlane_b32 s27, v252, 0
	s_add_u32 s14, s14, s27
	v_readlane_b32 s27, v254, 7
	s_addc_u32 s15, s15, s27
	s_waitcnt lgkmcnt(0)
	v_mov_b64_e32 v[2:3], 0x500
	v_cmp_lt_i64_e64 s[38:39], s[14:15], v[2:3]
	v_mov_b64_e32 v[2:3], 0x4ff
	v_cmp_gt_i64_e32 vcc, s[14:15], v[2:3]
	s_mov_b32 s27, s2
	s_cbranch_vccnz .LBB0_187
	s_ashr_i32 s15, s14, 31
	s_lshr_b32 s15, s15, 29
	s_add_i32 s15, s14, s15
	s_ashr_i32 s27, s15, 3
	s_and_b32 s15, s15, -8
	s_sub_i32 s14, s14, s15
	s_cmp_lt_i32 s14, 0
	s_movk_i32 s15, 0xa1
	s_cselect_b32 s15, s15, 0xa0
	s_mul_i32 s14, s14, s15
	s_add_i32 s14, s14, s27
	s_mul_hi_i32 s15, s14, 0x66666667
	s_lshr_b32 s27, s15, 31
	s_ashr_i32 s15, s15, 4
	s_add_i32 s15, s15, s27
	s_lshl_b32 s27, s15, 2
	s_sub_i32 s30, 0x80, s27
	s_min_i32 s30, s30, 4
	s_mul_i32 s15, s15, 40
	s_sub_i32 s14, s14, s15
	s_lshr_b32 s50, s14, 2
	s_and_b32 s14, s14, 3
	s_add_i32 s27, s27, s14
	s_mov_b32 s52, s27

;     __host__ __device__ bool next(int i, Unit& u) const {
;     ...
;         int wgid = (int)L; { const int q = nwg / NXCD, r = nwg % NXCD, xcd = wgid % NXCD, off = wgid / NXCD; wgid = (xcd < r ? xcd * (q + 1) : r * (q + 1) + (xcd - r) * q) + off; }
;         const int nig = WGM * nN, gid = wgid / nig, fm = gid * WGM, gsz = (nM - fm) < WGM ? (nM - fm) : WGM;
;         u.pm = fm + ((wgid % nig) % gsz); u.pn = (wgid % nig) / gsz; return true;
.LBB0_674:
	s_ashr_i32 s10, s14, 3
	s_add_i32 s10, s20, s10
	s_ashr_i32 s11, s10, 31
	s_lshr_b32 s11, s11, 28
	s_add_i32 s11, s10, s11
	s_ashr_i32 s14, s11, 4
	s_lshl_b32 s14, s14, 2
	s_sub_i32 s15, 0x80, s14
	s_min_i32 s15, s15, 4
	s_and_b32 s11, s11, -16
	s_sub_i32 s11, s10, s11
	s_lshr_b32 s10, s11, 2
	s_and_b32 s11, s11, 3
	s_add_i32 s14, s14, s11

;     __host__ __device__ bool next(int i, Unit& u) const {
;         const long L = (long)i * G + c; if (L >= nwg) return false;
;         int wgid = (int)L; { const int q = nwg / NXCD, r = nwg % NXCD, xcd = wgid % NXCD, off = wgid / NXCD; wgid = (xcd < r ? xcd * (q + 1) : r * (q + 1) + (xcd - r) * q) + off; }
;         const int nig = WGM * nN, gid = wgid / nig, fm = gid * WGM, gsz = (nM - fm) < WGM ? (nM - fm) : WGM;
;         u.pm = fm + ((wgid % nig) % gsz); u.pn = (wgid % nig) / gsz; return true;
.LBB0_778:
	s_add_i32 s27, s34, 1
	v_readlane_b32 s11, v254, 8
	s_mul_i32 s11, s27, s11
	s_mul_hi_u32 s15, s27, s26
	s_add_i32 s15, s15, s11
	s_mul_i32 s11, s27, s26
	v_readlane_b32 s20, v252, 0
	s_add_u32 s20, s11, s20
	v_readlane_b32 s11, v254, 7
	s_addc_u32 s21, s15, s11
	s_waitcnt lgkmcnt(0)
	v_mov_b64_e32 v[2:3], 0xb00
	v_cmp_lt_i64_e64 s[42:43], s[20:21], v[2:3]
	v_mov_b64_e32 v[2:3], 0xaff
	v_cmp_gt_i64_e32 vcc, s[20:21], v[2:3]
	s_mov_b32 s59, s58
	s_cbranch_vccnz .LBB0_780
	s_ashr_i32 s10, s20, 31
	s_lshr_b32 s10, s10, 29
	s_add_i32 s10, s20, s10
	s_ashr_i32 s11, s10, 3
	s_and_b32 s10, s10, -8
	s_sub_i32 s10, s20, s10
	s_cmp_lt_i32 s10, 0
	s_movk_i32 s14, 0x161
	s_cselect_b32 s14, s14, 0x160
	s_mul_i32 s10, s10, s14
	s_add_i32 s10, s10, s11
	s_mul_hi_i32 s11, s10, 0x2e8ba2e9
	s_lshr_b32 s14, s11, 31
	s_ashr_i32 s11, s11, 4
	s_add_i32 s11, s11, s14
	s_lshl_b32 s14, s11, 2
	s_sub_i32 s15, 0x80, s14
	s_min_i32 s15, s15, 4
	s_mulk_i32 s11, 0x58
	s_sub_i32 s11, s10, s11
	s_lshr_b32 s10, s11, 2
	s_and_b32 s11, s11, 3
	s_add_i32 s59, s14, s11
	s_mov_b32 s14, s59

;     __host__ __device__ bool next(int i, Unit& u) const {
;     ...
;         int wgid = (int)L; { const int q = nwg / NXCD, r = nwg % NXCD, xcd = wgid % NXCD, off = wgid / NXCD; wgid = (xcd < r ? xcd * (q + 1) : r * (q + 1) + (xcd - r) * q) + off; }
;         const int nig = WGM * nN, gid = wgid / nig, fm = gid * WGM, gsz = (nM - fm) < WGM ? (nM - fm) : WGM;
;         u.pm = fm + ((wgid % nig) % gsz); u.pn = (wgid % nig) / gsz; return true;
.LBB0_862:
	s_ashr_i32 s10, s14, 3
	s_add_i32 s10, s30, s10
	s_ashr_i32 s11, s10, 31
	s_lshr_b32 s11, s11, 28
	s_add_i32 s11, s10, s11
	s_ashr_i32 s14, s11, 4
	s_lshl_b32 s14, s14, 2
	s_sub_i32 s15, 0x80, s14
	s_min_i32 s15, s15, 4
	s_and_b32 s11, s11, -16
	s_sub_i32 s10, s10, s11
	s_lshr_b32 s57, s10, 2
	s_and_b32 s10, s10, 3
	s_add_i32 s58, s14, s10
